# P5 stage 1 (LoRA up-projections): XOR-swizzled w/a/g weight images (DMA source chunk permuted, conflict-free ds_read_b128) + all 18 fragment reads issued up front with counted lgkmcnt, interleaved q0/
# speedup vs baseline: 1.0091x; 1.0015x over previous
; #define GAS __attribute__((address_space(1)))
; #define LAS __attribute__((address_space(3)))
; __device__ __forceinline__ void rwkv_chunk_group(Frame& F, int bc, unsigned long long& tsub) {
;     ...
;     const float* PRM = (const float*)(F.ws + WS_PRM);
;     LAS unsigned char* L = F.lds;
;     const int tid = F.tid, lane = F.lane, w = F.wave, fr = lane & 15, fq = lane >> 4;
;     const int b = bc / NCH, c = bc % NCH;
;     const int row0 = b * T + c * CH;
;     const bf16* P = (const bf16*)(F.ws + WS_PRW);
;     const float* mu = (PRM + 0);
;     const f32x4 Z4 = (f32x4){0.f, 0.f, 0.f, 0.f};
; #pragma unroll 1
;     for (int i = 0; i < 5; ++i) { const int qd = tid + 512 * i; const int t = qd / 36, l0 = 8 * (qd % 36);
;         if (qd < CH * 36) {
;             const size_t off = (size_t)(row0 + t) * PRW + 1536 + l0; const v4u cur = *(const GAS v4u*)(P + off); v4u prv = (v4u){0u, 0u, 0u, 0u}; if (c * CH + t > 0) prv = *(const GAS v4u*)(P + off - PRW);
;             const f32x4 m0 = *(const f32x4*)(mu + 1536 + l0), m1 = *(const f32x4*)(mu + 1536 + l0 + 4);
;             float x[8];
; #pragma unroll
;             for (int e = 0; e < 4; ++e) { const unsigned cw = cur[e], pw = prv[e]; const float c0 = bflo(cw), c1 = bfhi(cw), p0 = bflo(pw), p1 = bfhi(pw);
;                 const float ma = (e < 2) ? m0[2 * e] : m1[2 * e - 4], mb = (e < 2) ? m0[2 * e + 1] : m1[2 * e - 3];
;                 x[2 * e] = c0 + (p0 - c0) * ma; x[2 * e + 1] = c1 + (p1 - c1) * mb; }
;             LAS unsigned char* dst;
;             if (l0 < 64) { dst = L + L_XW + t * LD + l0 * 2;
; #pragma unroll
;                 for (int e = 0; e < 8; ++e) x[e] = 1.f - 2.f * __builtin_amdgcn_rcpf(1.f + __expf(2.f * x[e])); }
;             else if (l0 < 128) { dst = L + L_XA + t * LD + (l0 - 64) * 2; }
;             else { dst = L + L_XG + t * 336 + (l0 - 128) * 2;
; #pragma unroll
;                 for (int e = 0; e < 8; ++e) x[e] = __builtin_amdgcn_rcpf(1.f + __expf(-x[e])); }
;             *(LAS v4u*)dst = (v4u){pk2(x[0], x[1]), pk2(x[2], x[3]), pk2(x[4], x[5]), pk2(x[6], x[7])};
;         } }
;     LBAR();
;     bf16x8 xw[2], xa[2], xg[5];
;     { const int m0 = 16 * (w >> 1);
; #pragma unroll
;       for (int k = 0; k < 2; ++k) { xw[k] = *(const LAS bf16x8*)(L + L_XW + (m0 + fr) * LD + fq * 16 + k * 64); xa[k] = *(const LAS bf16x8*)(L + L_XA + (m0 + fr) * LD + fq * 16 + k * 64); }
; #pragma unroll
.LBB0_1389:
	s_load_dwordx2 s[2:3], s[72:73], 0x108
	v_readlane_b32 s60, v254, 13
	v_readlane_b32 s61, v254, 14
	s_waitcnt lgkmcnt(0)
	s_cmp_lt_i32 s2, 6
	s_cselect_b64 s[0:1], -1, 0
	s_cmp_gt_i32 s3, 5
	s_cselect_b64 s[2:3], -1, 0
	s_and_b64 s[0:1], s[0:1], s[2:3]
	s_andn2_b64 vcc, exec, s[0:1]
	s_cbranch_vccnz .LBB0_1476
	v_readlane_b32 s0, v254, 2
	s_cmpk_gt_i32 s0, 0xff
	v_readlane_b32 s1, v254, 3
	s_cbranch_scc1 .LBB0_1476
	s_add_u32 s0, s86, 0x11800
	v_writelane_b32 v254, s82, 17
	s_addc_u32 s1, s87, 0
	v_writelane_b32 v254, s0, 18
	v_and_b32_e32 v6, 15, v208
	s_movk_i32 s2, 0x150
	v_writelane_b32 v254, s1, 19
	s_add_u32 s0, s86, 0x10000
	s_addc_u32 s1, s87, 0
	v_writelane_b32 v254, s0, 20
	s_add_i32 s33, 0, 0x12000
	s_add_i32 s4, 0, 0x14400
	v_writelane_b32 v254, s1, 21
	s_lshl_b32 s0, s93, 3
	s_and_b32 s1, s0, 0x1ffffff0
	v_or_b32_e32 v8, s1, v6
	v_mul_lo_u32 v0, v8, s2
	s_sub_i32 s2, 0, s0
	v_writelane_b32 v254, s2, 22
	v_writelane_b32 v254, s0, 23
	s_add_i32 s0, s0, -1
	v_writelane_b32 v254, s0, 24
	s_add_i32 s74, 0, 0x16800
	v_readlane_b32 s14, v254, 2
	s_lshl_b32 s0, s14, 6
	s_and_b32 s0, s0, 0x1c0
	s_lshl_b32 s2, s0, 1
	v_readlane_b32 s6, v254, 15
	v_readlane_b32 s7, v254, 16
	s_add_u32 s2, s6, s2
	s_addc_u32 s3, s7, 0
	s_add_u32 s75, s86, 0x100000
	v_ashrrev_i32_e32 v209, 31, v208
	s_addc_u32 s88, s87, 0
	v_add_u32_e32 v13, s74, v0
	v_lshlrev_b64 v[0:1], 1, v[208:209]
	s_cmpk_gt_u32 s79, 0x8ff
	v_lshl_add_u64 v[48:49], s[2:3], 0, v[0:1]
	s_cselect_b64 s[2:3], -1, 0
	v_readlane_b32 s15, v254, 3
	v_writelane_b32 v254, s2, 25
	s_cmpk_lt_u32 s79, 0x900
	v_ashrrev_i32_e32 v51, 2, v208
	v_writelane_b32 v254, s3, 26
	s_cselect_b64 s[2:3], -1, 0
	s_mov_b64 s[8:9], s[80:81]
	s_add_u32 s80, s86, 0x120000
	v_ashrrev_i32_e32 v59, 3, v208
	s_addc_u32 s81, s87, 0
	v_add_u32_e32 v55, s0, v51
	v_add_u32_e32 v104, s0, v59
	s_lshl_b32 s0, s93, 1
	v_writelane_b32 v254, s2, 27
	s_and_b32 s5, s0, 2
	s_add_i32 s89, 0, 0x20100
	v_writelane_b32 v254, s3, 28
	s_add_u32 s2, s86, 0x12000
	s_addc_u32 s3, s87, 0
	v_writelane_b32 v254, s2, 29
	v_lshl_add_u32 v58, v208, 1, 0
	v_lshl_add_u64 v[56:57], s[6:7], 0, v[0:1]
	v_writelane_b32 v254, s3, 30
	s_add_u32 s2, s86, 0x12800
	s_addc_u32 s3, s87, 0
	v_writelane_b32 v254, s2, 31
	s_mul_i32 s6, s93, 0x208
	v_add_lshl_u32 v119, v208, s6, 2
	v_writelane_b32 v254, s3, 32
	s_add_u32 s2, s86, 0x13000
	s_addc_u32 s3, s87, 0
	v_writelane_b32 v254, s2, 33
	v_ashrrev_i32_e32 v3, 4, v208
	v_lshlrev_b32_e32 v2, 3, v208
	v_writelane_b32 v254, s3, 34
	s_add_u32 s2, s86, 0x13800
	s_addc_u32 s3, s87, 0
	v_writelane_b32 v254, s2, 35
	v_and_b32_e32 v50, 24, v2
	v_and_b32_e32 v54, 56, v2
	v_writelane_b32 v254, s3, 36
	s_add_u32 s2, s86, 0x14000
	s_addc_u32 s3, s87, 0
	s_lshl_b32 s0, s93, 8
	v_writelane_b32 v254, s2, 37
	s_add_i32 s0, s0, 0
	s_add_i32 s0, s0, 0x1f800
	v_writelane_b32 v254, s3, 38
	v_writelane_b32 v254, s0, 39
	s_movk_i32 s0, 0x8e
	s_cmp_lt_u32 s79, 64
	v_mad_u64_u32 v[0:1], s[2:3], v208, s0, v[58:59]
	s_cselect_b64 s[82:83], -1, 0
	s_lshl_b32 s16, s93, 4
	s_add_i32 s2, 0, 0x18c00
	s_add_i32 s3, 0, 0x1d400
	s_lshl_b32 s94, s93, 9
	s_add_i32 s0, 0, 0x1b000
	s_lshl_b32 s11, s5, 4
	s_cmpk_gt_u32 s79, 0x7f
	s_cselect_b64 s[6:7], -1, 0
	v_writelane_b32 v254, s6, 40
	s_cmpk_gt_u32 s79, 0xbf
	v_lshlrev_b32_e32 v2, 2, v3
	v_writelane_b32 v254, s7, 41
	s_cselect_b64 s[6:7], -1, 0
	v_writelane_b32 v254, s6, 42
	s_cmpk_gt_u32 s79, 0xff
	v_add_u32_e32 v7, s1, v2
	v_writelane_b32 v254, s7, 43
	s_cselect_b64 s[6:7], -1, 0
	v_writelane_b32 v254, s6, 44
	s_cmpk_gt_u32 s79, 0x13f
	v_lshl_add_u32 v7, v7, 6, v7
	v_writelane_b32 v254, s7, 45
	s_cselect_b64 s[6:7], -1, 0
	v_writelane_b32 v254, s6, 46
	s_cmpk_gt_u32 s79, 0x17f
	v_or_b32_e32 v20, s11, v6
	v_writelane_b32 v254, s7, 47
	s_cselect_b64 s[6:7], -1, 0
	v_writelane_b32 v254, s6, 48
	s_cmpk_gt_u32 s79, 0x1bf
	v_add_u32_e32 v26, 0x41, v7
	v_writelane_b32 v254, s7, 49
	s_cselect_b64 s[6:7], -1, 0
	v_writelane_b32 v254, s6, 50
	s_cmpk_gt_u32 s79, 0x1ff
	v_add_u32_e32 v27, 0x82, v7
	v_writelane_b32 v254, s7, 51
	v_writelane_b32 v254, s79, 52
	s_cselect_b64 s[6:7], -1, 0
	v_add_u32_e32 v28, 0xc3, v7
	v_writelane_b32 v254, s6, 53
	v_mul_u32_u24_e32 v110, 0x90, v20
	v_lshlrev_b32_e32 v21, 7, v20
	v_lshlrev_b32_e32 v22, 6, v20
	v_or_b32_e32 v23, 16, v20
	v_add_lshl_u32 v111, v7, v20, 2
	v_add_lshl_u32 v112, v26, v20, 2
	v_add_lshl_u32 v113, v27, v20, 2
	v_add_lshl_u32 v114, v28, v20, 2
	v_writelane_b32 v254, s7, 54
	v_add_u32_e32 v20, s11, v2
	s_or_b32 s6, s5, 1
	v_lshlrev_b32_e32 v24, 7, v23
	v_lshlrev_b32_e32 v25, 6, v23
	v_add_lshl_u32 v115, v7, v23, 2
	v_add_lshl_u32 v116, v26, v23, 2
	v_add_lshl_u32 v117, v27, v23, 2
	v_add_lshl_u32 v118, v28, v23, 2
	v_or_b32_e32 v23, 1, v20
	s_lshl_b32 s12, s6, 4
	v_cmp_eq_u32_e64 s[18:19], v8, v20
	v_cmp_eq_u32_e64 s[20:21], v8, v23
	s_cmp_le_u32 s11, s1
	s_movk_i32 s10, 0x90
	v_cndmask_b32_e64 v7, 0, 1.0, s[18:19]
	v_cndmask_b32_e64 v26, 0, 1.0, s[20:21]
	s_cselect_b64 s[78:79], -1, 0
	s_cmp_ge_u32 s11, s1
	s_mov_b64 s[36:37], s[84:85]
	v_mul_lo_u32 v9, v8, s10
	v_cvt_pk_bf16_f32 v60, v7, v26
	v_add_u32_e32 v26, s12, v2
	s_mov_b64 s[38:39], s[86:87]
	s_cselect_b64 s[84:85], -1, 0
; #define LAS __attribute__((address_space(3)))
; __device__ __forceinline__ void lora_dma(const bf16* lora, int h, unsigned lds0, int w, int lane) {
;     for (int p = w; p < 36; p += NWAVES) {
;         const bf16* src; unsigned dst;
;         if (p < 16) { const int row = 8 * (p & 7) + (lane >> 3); src = lora + (p >= 8 ? 512 * 64 : 0) + (size_t)(h * 64 + row) * 64 + (lane & 7) * 8; dst = lds0 + L_LWA + p * 1024; }
;         else { const int q = p - 16, ks = q >> 2, row = 16 * (q & 3) + (lane >> 2); src = lora + 2 * 512 * 64 + (size_t)(h * 64 + row) * 160 + ks * 32 + (lane & 3) * 8; dst = lds0 + L_LG + q * 1024; }
;         attn_body::glds16(src, (unsigned)__builtin_amdgcn_readfirstlane(dst));
;     }
; }
; __device__ __forceinline__ void rwkv_chunk_group(Frame& F, int bc, unsigned long long& tsub) {
;     ...
;     { const int m0 = 16 * (w >> 1);
; #pragma unroll
;       for (int k = 0; k < 2; ++k) { xw[k] = *(const LAS bf16x8*)(L + L_XW + (m0 + fr) * LD + fq * 16 + k * 64); xa[k] = *(const LAS bf16x8*)(L + L_XA + (m0 + fr) * LD + fq * 16 + k * 64); }
; #pragma unroll
;       for (int k = 0; k < 5; ++k) xg[k] = *(const LAS bf16x8*)(L + L_XG + (m0 + fr) * 336 + fq * 16 + k * 64); }
;     const int ch = lane, tb = 8 * w;
;     bf16 raw[9][3];
;     { const bool has = (c * CH + tb > 0);
; #pragma unroll
;       for (int tt = 0; tt < 9; ++tt) { const size_t off = (size_t)(row0 + tb + tt - 1) * PRW + (F.vcu & (RW_H - 1)) * 64 + ch;
;           if (tt > 0 || has) { raw[tt][0] = P[off]; raw[tt][1] = P[off + 512]; raw[tt][2] = P[off + 1024]; } else { raw[tt][0] = 0; raw[tt][1] = 0; raw[tt][2] = 0; } } }
;     const bf16* lora = (const bf16*)(F.ws + WS_LORA);
;     LBAR();
;     const unsigned lds0 = (unsigned)(uintptr_t)L;
;     lora_dma(lora, F.vcu & (RW_H - 1), lds0, w, lane);
;     TSUB(0);
;     for (int hh = 0; hh < RW_H; ++hh) {
;     const int h = (hh + F.vcu) & (RW_H - 1), hnext = (hh + 1 + F.vcu) & (RW_H - 1);
;     const int item = (b * RW_H + h) * NCH + c;
;     {
;         asm volatile("s_waitcnt vmcnt(0)" ::: "memory"); LBAR();
;         f32x4 aw[2], aa[2], ag[2];
; #pragma unroll
;         for (int q = 0; q < 2; ++q) { const int n0 = 16 * ((2 * w + q) & 3); aw[q] = Z4; aa[q] = Z4; ag[q] = Z4;
;             const LAS unsigned char* wp = L + L_LWA + (n0 + fr) * 128 + fq * 16; const LAS unsigned char* gp = L + L_LG + (n0 + fr) * 64 + fq * 16;
	s_cmp_le_u32 s12, s1
	s_mov_b32 s95, 0
	v_lshl_add_u32 v16, v3, 3, v9
	v_mul_lo_u32 v31, v20, s10
	v_mul_lo_u32 v35, v26, s10
	s_cselect_b64 s[86:87], -1, 0
	s_cmp_ge_u32 s12, s1
	v_add_u32_e32 v12, s4, v9
	v_lshlrev_b32_e32 v4, 6, v208
	v_add_u32_e32 v32, s4, v31
	v_add_u32_e32 v36, s4, v35
	s_cselect_b64 s[90:91], -1, 0
	v_lshl_add_u32 v37, s5, 5, v16
	s_lshl_b64 s[4:5], s[94:95], 1
	v_ashrrev_i32_e32 v5, 31, v4
	s_add_u32 s4, s8, s4
	v_mov_b32_e32 v53, 0
	v_or_b32_e32 v7, s12, v6
	v_writelane_b32 v254, s8, 55
	s_addc_u32 s5, s9, s5
	v_lshlrev_b32_e32 v52, 6, v6
	s_mov_b32 s17, s95
	v_lshl_add_u64 v[4:5], v[4:5], 1, s[38:39]
	v_mul_u32_u24_e32 v128, 0x90, v7
	v_lshl_add_u64 v[6:7], s[4:5], 0, v[52:53]
	v_lshl_add_u64 v[4:5], v[4:5], 0, s[16:17]
	s_mov_b64 s[4:5], 0xc000000
	v_ashrrev_i32_e32 v3, 31, v2
	v_lshl_add_u64 v[62:63], v[4:5], 0, s[4:5]
	s_mov_b64 s[4:5], 0xd000000
	v_lshlrev_b32_e32 v52, 7, v8
	v_or_b32_e32 v27, 2, v20
	v_or_b32_e32 v29, 3, v20
	v_lshlrev_b64 v[2:3], 1, v[2:3]
	v_lshl_add_u64 v[64:65], v[4:5], 0, s[4:5]
	v_lshl_add_u64 v[4:5], s[38:39], 0, v[52:53]
	v_cmp_eq_u32_e64 s[22:23], v8, v27
	v_cmp_eq_u32_e64 s[24:25], v8, v29
	v_lshl_add_u64 v[4:5], v[4:5], 0, v[2:3]
	s_mov_b64 s[4:5], 0xe000000
	v_cmp_lt_i32_e32 vcc, v27, v8
	v_cndmask_b32_e64 v28, 0, 1.0, s[22:23]
	v_cndmask_b32_e64 v30, 0, 1.0, s[24:25]
	v_or_b32_e32 v34, 2, v26
	v_or_b32_e32 v39, 3, v26
	v_lshl_add_u64 v[66:67], v[4:5], 0, s[4:5]
	s_mov_b64 s[4:5], 0xf000000
	v_cmp_lt_i32_e64 s[36:37], v29, v8
	v_and_b32_e32 v11, -16, v208
	v_cvt_pk_bf16_f32 v61, v28, v30
	v_or_b32_e32 v30, 1, v26
	v_cmp_eq_u32_e64 s[30:31], v8, v34
	v_lshl_add_u64 v[68:69], v[4:5], 0, s[4:5]
	s_mov_b64 s[4:5], 0x4000000
	v_cmp_eq_u32_e64 s[34:35], v8, v39
	s_or_b64 s[38:39], s[36:37], vcc
	v_cmp_lt_i32_e32 vcc, v23, v8
	v_add_u32_e32 v106, 0, v11
	v_lshlrev_b32_e32 v18, 2, v8
	v_cmp_eq_u32_e64 s[26:27], v8, v26
	v_cmp_eq_u32_e64 s[28:29], v8, v30
	v_writelane_b32 v254, s9, 56
	v_cndmask_b32_e64 v38, 0, 1.0, s[30:31]
	v_lshl_add_u64 v[70:71], v[4:5], 0, s[4:5]
	v_cndmask_b32_e64 v4, 0, 1.0, s[34:35]
	s_mov_b32 s4, s16
	s_or_b64 s[40:41], s[38:39], vcc
	v_cmp_lt_i32_e32 vcc, v34, v8
	v_cmp_lt_i32_e64 s[42:43], v39, v8
	v_add_u32_e32 v10, s33, v9
	v_add_u32_e32 v14, s33, v11
	v_add_u32_e32 v15, s89, v11
	v_add_u32_e32 v107, v106, v9
	v_lshlrev_b32_e32 v1, 1, v8
	v_add_u32_e32 v17, s3, v9
	v_add_u32_e32 v19, s0, v9
	v_lshl_add_u32 v127, v20, 1, v9
	v_cndmask_b32_e64 v28, 0, 1.0, s[26:27]
	v_cndmask_b32_e64 v33, 0, 1.0, s[28:29]
	v_lshl_add_u32 v129, v26, 1, v9
	v_cvt_pk_bf16_f32 v73, v38, v4
	v_add_u32_e32 v4, s74, v9
	v_add_u32_e32 v5, 0, v31
	v_add_u32_e32 v9, 0, v35
	v_lshl_add_u32 v16, s6, 5, v16
	v_writelane_b32 v254, s4, 57
	v_add_u32_e32 v141, s16, v0
	v_add_u32_e32 v0, 0, v18
	s_or_b64 s[44:45], s[42:43], vcc
	v_cmp_lt_i32_e32 vcc, v30, v8
	v_lshlrev_b32_e32 v105, 2, v208
	v_add_u32_e32 v108, s74, v11
	v_add_u32_e32 v109, s2, v11
	v_add_u32_e32 v120, 0x104, v119
	v_add_u32_e32 v121, 0x208, v119
	v_add_u32_e32 v122, 0x30c, v119
	v_add_u32_e32 v123, 0x410, v119
	v_add_u32_e32 v124, 0x514, v119
	v_add_u32_e32 v125, 0x618, v119
	v_add_u32_e32 v126, 0x71c, v119
	v_cvt_pk_bf16_f32 v72, v28, v33
	v_add_u32_e32 v130, 0x12000, v106
	v_add_u32_e32 v131, 0x14400, v106
	v_add_u32_e32 v132, 0x12000, v107
	v_add_u32_e32 v133, 0x12040, v107
	v_lshl_add_u64 v[74:75], v[6:7], 0, v[2:3]
	v_add_u32_e32 v134, v10, v11
	v_add_u32_e32 v135, v12, v11
	v_add_u32_e32 v136, v13, v11
	v_add_u32_e32 v137, v14, v21
	v_add_u32_e32 v138, v15, v22
	v_add_u32_e32 v139, v14, v24
	v_add_u32_e32 v140, v15, v25
	v_and_b32_e32 v252, 7, v208
	v_lshlrev_b32_e32 v252, 4, v252
	v_xor_b32_e32 v137, v137, v252
	v_xor_b32_e32 v139, v139, v252
	v_bfe_u32 v252, v208, 2, 2
	v_lshlrev_b32_e32 v253, 1, v252
	v_and_b32_e32 v253, 2, v253
	v_xor_b32_e32 v252, v252, v253
	v_lshlrev_b32_e32 v252, 4, v252
	v_xor_b32_e32 v138, v138, v252
	v_xor_b32_e32 v140, v140, v252
	v_and_b32_e32 v252, 56, v208
	v_xor_b32_e32 v54, v54, v252
	v_bfe_u32 v252, v208, 4, 2
	v_lshlrev_b32_e32 v253, 1, v252
	v_and_b32_e32 v253, 2, v253
	v_xor_b32_e32 v252, v252, v253
	v_lshlrev_b32_e32 v252, 3, v252
	v_xor_b32_e32 v50, v50, v252
	v_writelane_b32 v254, s5, 58
	v_add_u32_e32 v142, 0, v37
	v_add_u32_e32 v143, 0, v16
	v_add_u32_e32 v144, v17, v11
	v_add_u32_e32 v145, 0x20000, v0
	v_add_u32_e32 v146, v19, v11
	v_mov_b32_e32 v147, 0x41b17218
	v_add_u32_e32 v148, v32, v1
	s_or_b64 s[46:47], s[44:45], vcc
	v_add_u32_e32 v149, v36, v1
	v_add_u32_e32 v150, v4, v11
	v_add_u32_e32 v151, v5, v1
	v_add_u32_e32 v152, v9, v1
	s_mov_b32 s1, 0xbfb8aa3b
	s_movk_i32 s4, 0x140
	s_mov_b32 s5, 0x5040100
	s_add_i32 s6, 0, 0x16100
	s_add_i32 s7, 0, 0x1a200
	s_mov_b32 s8, 0x800000
	s_mov_b32 s9, 0x3f317217
	s_mov_b32 s10, 0x7f800000
	s_lshl_b32 s76, s11, 1
	s_lshl_b32 s92, s12, 1
	s_mov_b32 s11, s14
	v_cmp_lt_i32_e64 s[48:49], v8, v20
	v_cmp_lt_i32_e64 s[50:51], v20, v8
	v_cmp_lt_i32_e64 s[52:53], v8, v27
	v_cmp_lt_i32_e64 s[54:55], v8, v29
	v_cmp_lt_i32_e64 s[56:57], v8, v26
	v_cmp_lt_i32_e64 s[58:59], v26, v8
	v_cmp_lt_i32_e64 s[60:61], v8, v34
	v_cmp_lt_i32_e64 s[62:63], v8, v39
	s_branch .LBB0_1393

; #define LAS __attribute__((address_space(3)))
; #define LBAR() asm volatile("s_waitcnt lgkmcnt(0)\n\ts_barrier" ::: "memory")
; #define TSUB(k) do { } while (0)
; __device__ __forceinline__ void rwkv_chunk_group(Frame& F, int bc, unsigned long long& tsub) {
;     ...
;         asm volatile("s_waitcnt vmcnt(0)" ::: "memory"); LBAR();
;         f32x4 aw[2], aa[2], ag[2];
; #pragma unroll
;         for (int q = 0; q < 2; ++q) { const int n0 = 16 * ((2 * w + q) & 3); aw[q] = Z4; aa[q] = Z4; ag[q] = Z4;
;             const LAS unsigned char* wp = L + L_LWA + (n0 + fr) * 128 + fq * 16; const LAS unsigned char* gp = L + L_LG + (n0 + fr) * 64 + fq * 16;
; #pragma unroll
;             for (int k = 0; k < 2; ++k) { aw[q] = __builtin_amdgcn_mfma_f32_16x16x32_bf16(xw[k], *(const LAS bf16x8*)(wp + k * 64), aw[q], 0, 0, 0); aa[q] = __builtin_amdgcn_mfma_f32_16x16x32_bf16(xa[k], *(const LAS bf16x8*)(wp + 8192 + k * 64), aa[q], 0, 0, 0); }
; #pragma unroll
;             for (int k = 0; k < 5; ++k) ag[q] = __builtin_amdgcn_mfma_f32_16x16x32_bf16(xg[k], *(const LAS bf16x8*)(gp + k * 4096), ag[q], 0, 0, 0);
;         }
;         LBAR();
; #pragma unroll
;         for (int q = 0; q < 2; ++q) { const int tw = 2 * w + q, m0 = 16 * (tw >> 2), n0 = 16 * (tw & 3);
; #pragma unroll
;             for (int v = 0; v < 4; ++v) { const int t = m0 + 4 * fq + v, cc = n0 + fr;
;                 *(LAS float*)(L + L_WL + (t * 65 + cc) * 4) = aw[q][v]; *(LAS float*)(L + L_AL + (t * 65 + cc) * 4) = aa[q][v]; *(LAS float*)(L + L_GL + (t * 65 + cc) * 4) = ag[q][v]; } }
;         LBAR();
;     }
;     TSUB(1);
;     {
;         const int gc = h * 64 + ch;
;         const float mur = mu[gc], muk = mu[512 + gc], muv = mu[1024 + gc];
;         const float w0 = (PRM + 2048)[gc], a0 = (PRM + 2560)[gc], k_k = (PRM + 3072)[gc], k_a = (PRM + 3584)[gc], r_k = (PRM + 4096)[gc];
.LBB0_1412:
	s_waitcnt vmcnt(8)
	v_perm_b32 v160, v203, v202, s5
	v_perm_b32 v161, v216, v215, s5
	v_perm_b32 v166, v204, v203, s5
	v_perm_b32 v167, v217, v216, s5
	v_perm_b32 v168, v206, v205, s5
	v_perm_b32 v169, v219, v218, s5
	v_perm_b32 v170, v212, v207, s5
	v_perm_b32 v171, v221, v220, s5
	v_perm_b32 v165, v214, v213, s5
	v_perm_b32 v172, v223, v222, s5
	v_readlane_b32 s98, v254, 2
	v_readlane_b32 s100, v254, 20
	v_readlane_b32 s101, v254, 21
	s_add_i32 s98, s98, s12
	s_lshl_b32 s98, s98, 6
	s_and_b32 s98, s98, 0x1c0
	v_add_lshl_u32 v238, v208, s98, 2
	v_mov_b32_e32 v239, 0
	s_nop 0
	v_lshl_add_u64 v[232:233], s[100:101], 0, v[238:239]
	s_mov_b64 s[100:101], 0x2000
	v_lshl_add_u64 v[234:235], v[232:233], 0, s[100:101]
	s_mov_b64 s[100:101], 0x3800
	v_lshl_add_u64 v[236:237], v[232:233], 0, s[100:101]
	global_load_dword v224, v[232:233], off
	global_load_dword v225, v[232:233], off offset:2048
	global_load_dword v226, v[234:235], off offset:-4096
	global_load_dword v227, v[234:235], off
	global_load_dword v228, v[234:235], off offset:2048
	global_load_dword v229, v[236:237], off offset:-2048
	global_load_dword v230, v[236:237], off
	global_load_dword v231, v[236:237], off offset:2048
	s_waitcnt lgkmcnt(0)
	s_barrier
	v_xor_b32_e32 v252, 64, v137
	v_xor_b32_e32 v253, 64, v139
	ds_read_b128 v[36:39], v137
	ds_read_b128 v[76:79], v139
	ds_read_b128 v[98:101], v252
	ds_read_b128 v[174:177], v253
	ds_read_b128 v[40:43], v137 offset:8192
	ds_read_b128 v[80:83], v139 offset:8192
	ds_read_b128 v[178:181], v252 offset:8192
	ds_read_b128 v[182:185], v253 offset:8192
	ds_read_b128 v[44:47], v138
	ds_read_b128 v[84:87], v140
	ds_read_b128 v[186:189], v138 offset:4096
	ds_read_b128 v[232:235], v140 offset:4096
	ds_read_b128 v[236:239], v138 offset:8192
	ds_read_b128 v[240:243], v140 offset:8192
	ds_read_b128 v[244:247], v138 offset:12288
	s_waitcnt lgkmcnt(14)
	v_mfma_f32_16x16x32_bf16 v[36:39], v[0:3], v[36:39], 0
	ds_read_b128 v[248:251], v140 offset:12288
	v_add_u32_e32 v52, s33, v111
	s_mov_b32 s68, s12
	s_waitcnt lgkmcnt(14)
	v_mfma_f32_16x16x32_bf16 v[76:79], v[0:3], v[76:79], 0
	ds_read_b128 v[88:91], v138 offset:16384
	v_readlane_b32 s12, v254, 2
	s_add_i32 s14, s68, s12
	s_waitcnt lgkmcnt(14)
	v_mfma_f32_16x16x32_bf16 v[36:39], v[4:7], v[98:101], v[36:39]
	ds_read_b128 v[98:101], v140 offset:16384
	s_lshl_b32 s14, s14, 6
	s_waitcnt lgkmcnt(14)
	v_mfma_f32_16x16x32_bf16 v[76:79], v[4:7], v[174:177], v[76:79]
	s_and_b32 s14, s14, 0x1c0
	s_waitcnt lgkmcnt(13)
	v_mfma_f32_16x16x32_bf16 v[40:43], v[8:11], v[40:43], 0
	s_add_i32 s66, s11, s14
	s_waitcnt lgkmcnt(12)
	v_mfma_f32_16x16x32_bf16 v[80:83], v[8:11], v[80:83], 0
	v_add_u32_e32 v191, s6, v125
	s_waitcnt lgkmcnt(11)
	v_mfma_f32_16x16x32_bf16 v[40:43], v[12:15], v[178:181], v[40:43]
	v_readlane_b32 s13, v254, 3
	s_waitcnt lgkmcnt(10)
	v_mfma_f32_16x16x32_bf16 v[80:83], v[12:15], v[182:185], v[80:83]
	s_mov_b32 s64, s12
	s_waitcnt lgkmcnt(9)
	v_mfma_f32_16x16x32_bf16 v[44:47], v[16:19], v[44:47], 0
	s_add_i32 s12, s68, 1
	s_waitcnt lgkmcnt(8)
	v_mfma_f32_16x16x32_bf16 v[84:87], v[16:19], v[84:87], 0
	s_add_i32 s13, s12, s64
	s_waitcnt lgkmcnt(7)
	v_mfma_f32_16x16x32_bf16 v[44:47], v[20:23], v[186:189], v[44:47]
	v_add_u32_e32 v96, s6, v124
	s_waitcnt lgkmcnt(6)
	v_mfma_f32_16x16x32_bf16 v[84:87], v[20:23], v[232:235], v[84:87]
	v_add_u32_e32 v93, s7, v123
	s_waitcnt lgkmcnt(5)
	v_mfma_f32_16x16x32_bf16 v[44:47], v[24:27], v[236:239], v[44:47]
	v_add_u32_e32 v97, s7, v124
	s_waitcnt lgkmcnt(4)
	v_mfma_f32_16x16x32_bf16 v[84:87], v[24:27], v[240:243], v[84:87]
	v_add_u32_e32 v192, s7, v125
	s_waitcnt lgkmcnt(3)
	v_mfma_f32_16x16x32_bf16 v[44:47], v[28:31], v[244:247], v[44:47]
	v_lshlrev_b32_e32 v197, 16, v162
	s_waitcnt lgkmcnt(2)
	v_mfma_f32_16x16x32_bf16 v[84:87], v[28:31], v[248:251], v[84:87]
	v_and_b32_e32 v199, 0xffff0000, v172
	s_waitcnt lgkmcnt(1)
	v_mfma_f32_16x16x32_bf16 v[44:47], v[32:35], v[88:91], v[44:47]
	s_ashr_i32 s67, s66, 31
	s_waitcnt lgkmcnt(0)
	v_mfma_f32_16x16x32_bf16 v[84:87], v[32:35], v[98:101], v[84:87]
	s_and_b32 s13, s13, 7
	s_nop 7
	s_nop 7
	s_waitcnt lgkmcnt(0)
	s_barrier
	ds_write_b32 v52, v36
	v_add_u32_e32 v36, s6, v111
	ds_write_b32 v36, v40
	v_add_u32_e32 v36, s7, v111
	ds_write_b32 v36, v44
	v_add_u32_e32 v36, s33, v112
	ds_write_b32 v36, v37
	v_add_u32_e32 v36, s6, v112
	ds_write_b32 v36, v41
	v_add_u32_e32 v36, s7, v112
	ds_write_b32 v36, v45
	v_add_u32_e32 v36, s33, v113
	ds_write_b32 v36, v38
	v_add_u32_e32 v36, s6, v113
	ds_write_b32 v36, v42
	v_add_u32_e32 v36, s7, v113
	ds_write_b32 v36, v46
	v_add_u32_e32 v36, s33, v114
	ds_write_b32 v36, v39
	v_add_u32_e32 v36, s6, v114
	ds_write_b32 v36, v43
	v_add_u32_e32 v36, s7, v114
	ds_write_b32 v36, v47
	v_add_u32_e32 v36, s33, v115
	ds_write_b32 v36, v76
	v_add_u32_e32 v36, s6, v115
	ds_write_b32 v36, v80
	v_add_u32_e32 v36, s7, v115
	ds_write_b32 v36, v84
	v_add_u32_e32 v36, s33, v116
	ds_write_b32 v36, v77
	v_add_u32_e32 v36, s6, v116
	ds_write_b32 v36, v81
	v_add_u32_e32 v36, s7, v116
	ds_write_b32 v36, v85
	v_add_u32_e32 v36, s33, v117
	ds_write_b32 v36, v78
	v_add_u32_e32 v36, s6, v117
	ds_write_b32 v36, v82
	v_add_u32_e32 v36, s7, v117
	ds_write_b32 v36, v86
	v_add_u32_e32 v36, s33, v118
	ds_write_b32 v36, v79
	v_add_u32_e32 v36, s6, v118
	ds_write_b32 v36, v83
	v_add_u32_e32 v36, s7, v118
	ds_write_b32 v36, v87
	v_add_u32_e32 v36, s14, v208
	v_ashrrev_i32_e32 v37, 31, v36
	v_readlane_b32 s14, v254, 20
	v_lshlrev_b64 v[36:37], 2, v[36:37]
	v_readlane_b32 s15, v254, 21
	s_waitcnt lgkmcnt(0)
	s_barrier
; #define LAS __attribute__((address_space(3)))
; __device__ __forceinline__ float sigmoidf_(float x) { return __builtin_amdgcn_rcpf(1.0f + __expf(-x)); }
; __device__ __forceinline__ void rwkv_chunk_group(Frame& F, int bc, unsigned long long& tsub) {
;     ...
;         const int gc = h * 64 + ch;
;         const float mur = mu[gc], muk = mu[512 + gc], muv = mu[1024 + gc];
;         const float w0 = (PRM + 2048)[gc], a0 = (PRM + 2560)[gc], k_k = (PRM + 3072)[gc], k_a = (PRM + 3584)[gc], r_k = (PRM + 4096)[gc];
;         float rr[8], kp[8], vv[8], aa[8], bb[8], ld[8], vbv[8], ggv[8];
;         float pr = bf2f(raw[0][0]), pk = bf2f(raw[0][1]), pv = bf2f(raw[0][2]);
;         bf16* VBp = (bf16*)(F.ws + WS_VB) + (size_t)item * 4096; bf16* Gp = (bf16*)(F.ws + WS_G) + (size_t)item * 4096;
;         float run = 0.f; float kkv[8], icv[8], sq[8], bq[8];
; #pragma unroll
;         for (int tt = 0; tt < 8; ++tt) { const int t = tb + tt;
;             const float cr = bf2f(raw[tt + 1][0]), ck = bf2f(raw[tt + 1][1]), cv = bf2f(raw[tt + 1][2]);
;             const float r = cr + (pr - cr) * mur, k = ck + (pk - ck) * muk, v = cv + (pv - cv) * muv; pr = cr; pk = ck; pv = cv;
;             const float wl = *(const LAS float*)(L + L_WL + (t * 65 + ch) * 4), al = *(const LAS float*)(L + L_AL + (t * 65 + ch) * 4), gl = *(const LAS float*)(L + L_GL + (t * 65 + ch) * 4);
;             const float z = -(w0 + wl); const float sp = fmaxf(z, 0.f) + __logf(1.f + __expf(-fabsf(z)));
;             const float lgd = -__expf(-sp - 0.5f);
;             const float ic = sigmoidf_(a0 + al);
;             const float kv = k * k_k; const float kq = k * (1.f + (ic - 1.f) * k_a);
;             kkv[tt] = kv; icv[tt] = ic; sq[tt] = kv * kv; bq[tt] = r * kq * r_k;
;             rr[tt] = r; kp[tt] = kq; vv[tt] = v; run += lgd; ld[tt] = run; ggv[tt] = gl;
;         }
	v_add_u32_e32 v41, s7, v120
	v_add_u32_e32 v87, s7, v122
	v_lshl_add_u64 v[38:39], s[14:15], 0, v[36:37]
	s_waitcnt vmcnt(0)
	v_mov_b32_e32 v95, v224
	v_mov_b32_e32 v42, v225
	s_movk_i32 s14, 0x1000
	v_add_co_u32_e32 v38, vcc, s14, v38
	v_readlane_b32 s14, v254, 29
	s_nop 0
	v_addc_co_u32_e32 v39, vcc, 0, v39, vcc
	v_readlane_b32 s15, v254, 30
	v_mov_b32_e32 v52, v226
	v_add_u32_e32 v83, s7, v121
	v_lshl_add_u64 v[38:39], s[14:15], 0, v[36:37]
	v_mov_b32_e32 v45, v227
	v_readlane_b32 s14, v254, 31
	v_readlane_b32 s15, v254, 32
	v_lshlrev_b32_e32 v82, 16, v155
	v_and_b32_e32 v77, 0xffff0000, v167
	v_lshl_add_u64 v[38:39], s[14:15], 0, v[36:37]
	v_mov_b32_e32 v43, v228
	v_readlane_b32 s14, v254, 33
	v_readlane_b32 s15, v254, 34
	v_lshlrev_b32_e32 v76, 16, v167
	v_and_b32_e32 v79, 0xffff0000, v166
	v_lshl_add_u64 v[38:39], s[14:15], 0, v[36:37]
	v_readlane_b32 s14, v254, 35
	v_readlane_b32 s15, v254, 36
	v_mov_b32_e32 v44, v229
	v_lshlrev_b32_e32 v78, 16, v166
	v_lshl_add_u64 v[38:39], s[14:15], 0, v[36:37]
	v_mov_b32_e32 v46, v230
	v_readlane_b32 s14, v254, 37
	v_readlane_b32 s15, v254, 38
	v_lshlrev_b32_e32 v86, 16, v157
	v_and_b32_e32 v91, 0xffff0000, v168
	v_lshl_add_u64 v[36:37], s[14:15], 0, v[36:37]
	v_mov_b32_e32 v103, v231
	v_lshlrev_b32_e32 v36, 16, v153
	v_lshlrev_b32_e32 v37, 16, v154
	v_sub_f32_e32 v36, v36, v37
	v_add_u32_e32 v38, s6, v119
	v_add_u32_e32 v39, s7, v119
	ds_read_b32 v38, v38
	ds_read_b32 v47, v39
	ds_read_b32 v177, v41
	ds_read_b32 v185, v87
	ds_read_b32 v191, v191
	v_lshlrev_b32_e32 v90, 16, v168
	v_and_b32_e32 v85, 0xffff0000, v169
	ds_read_b32 v182, v83
	ds_read_b32 v96, v96
	ds_read_b32 v189, v93
	ds_read_b32 v193, v97
	ds_read_b32 v194, v192
	s_waitcnt vmcnt(7)
	v_fma_f32 v173, v36, v95, v37
	v_add_u32_e32 v36, s33, v119
	ds_read_b32 v36, v36
	s_waitcnt vmcnt(4) lgkmcnt(0)
	v_add_f32_e32 v36, v45, v36
	v_max_f32_e64 v39, -v36, 0
	v_mul_f32_e64 v36, |v36|, s1
	v_exp_f32_e32 v36, v36
	s_nop 0
	v_add_f32_e32 v36, 1.0, v36
	v_cmp_gt_f32_e32 vcc, s8, v36
	s_nop 1
	v_cndmask_b32_e64 v40, 0, 32, vcc
	v_ldexp_f32 v36, v36, v40
	v_log_f32_e32 v36, v36
	s_nop 0
	v_mul_f32_e32 v40, 0x3f317217, v36
	v_fma_f32 v40, v36, s9, -v40
	v_fmac_f32_e32 v40, 0x3377d1cf, v36
	v_fmac_f32_e32 v40, 0x3f317217, v36
	v_cmp_lt_f32_e64 s[64:65], |v36|, s10
	s_nop 1
	v_cndmask_b32_e64 v36, v36, v40, s[64:65]
	v_cndmask_b32_e32 v40, 0, v147, vcc
	v_sub_f32_e32 v36, v36, v40
	v_add_f32_e32 v36, v39, v36
	v_add_u32_e32 v39, s33, v120
	ds_read_b32 v39, v39
	v_sub_f32_e32 v36, -0.5, v36
	v_mul_f32_e32 v36, 0x3fb8aa3b, v36
	v_exp_f32_e32 v102, v36
	s_waitcnt vmcnt(3)
	v_add_f32_e32 v36, v43, v38
	v_mul_f32_e32 v36, 0xbfb8aa3b, v36
	v_add_u32_e32 v40, s6, v120
	v_exp_f32_e32 v36, v36
	ds_read_b32 v40, v40
	s_waitcnt lgkmcnt(1)
	v_add_f32_e32 v39, v45, v39
	v_max_f32_e64 v41, -v39, 0
	v_mul_f32_e64 v39, |v39|, s1
	v_exp_f32_e32 v39, v39
	v_add_f32_e32 v36, 1.0, v36
	v_rcp_f32_e32 v38, v36
	v_sub_f32_e32 v36, v37, v82
	v_fma_f32 v174, v36, v95, v82
	v_and_b32_e32 v37, 0xffff0000, v161
	v_lshlrev_b32_e32 v36, 16, v161
	v_add_f32_e32 v39, 1.0, v39
	v_pk_add_f32 v[36:37], v[36:37], v[76:77] neg_lo:[0,1] neg_hi:[0,1]
	v_cmp_gt_f32_e32 vcc, s8, v39
	v_pk_fma_f32 v[36:37], v[36:37], v[52:53], v[76:77] op_sel_hi:[1,0,1]
	s_nop 0
	v_cndmask_b32_e64 v76, 0, 32, vcc
	v_ldexp_f32 v39, v39, v76
	v_log_f32_e32 v39, v39
	s_nop 0
	v_mul_f32_e32 v76, 0x3f317217, v39
	v_fma_f32 v76, v39, s9, -v76
	v_fmac_f32_e32 v76, 0x3377d1cf, v39
	v_fmac_f32_e32 v76, 0x3f317217, v39
	v_cmp_lt_f32_e64 s[64:65], |v39|, s10
	s_nop 1
	v_cndmask_b32_e64 v39, v39, v76, s[64:65]
	v_cndmask_b32_e32 v76, 0, v147, vcc
	v_sub_f32_e32 v39, v39, v76
	v_add_f32_e32 v39, v41, v39
	v_sub_f32_e32 v39, -0.5, v39
	v_mul_f32_e32 v39, 0x3fb8aa3b, v39
	v_exp_f32_e32 v76, v39
	s_waitcnt lgkmcnt(0)
	v_add_f32_e32 v39, v43, v40
	v_mul_f32_e32 v39, 0xbfb8aa3b, v39
	v_exp_f32_e32 v39, v39
	v_and_b32_e32 v41, 0xffff0000, v160
	v_lshlrev_b32_e32 v40, 16, v160
	v_pk_add_f32 v[40:41], v[40:41], v[78:79] neg_lo:[0,1] neg_hi:[0,1]
	v_add_f32_e32 v39, 1.0, v39
	v_rcp_f32_e32 v39, v39
	v_pk_fma_f32 v[80:81], v[40:41], v[42:43], v[78:79] op_sel_hi:[1,0,1]
	v_sub_f32_e64 v176, -v102, v76
	v_lshlrev_b32_e32 v76, 16, v156
	v_pk_add_f32 v[40:41], v[38:39], -1.0 op_sel_hi:[1,0]
	s_waitcnt vmcnt(1)
	v_pk_fma_f32 v[40:41], v[46:47], v[40:41], 1.0 op_sel_hi:[0,1,0]
	v_pk_mul_f32 v[40:41], v[80:81], v[40:41]
	s_nop 0
	v_mul_f32_e32 v78, v173, v40
	s_waitcnt vmcnt(0)
	v_mul_f32_e32 v101, v103, v78
	v_mul_f32_e32 v78, v174, v41
	v_mul_f32_e32 v100, v103, v78
	v_sub_f32_e32 v78, v82, v76
	v_fma_f32 v175, v78, v95, v76
	v_add_u32_e32 v78, s33, v121
	ds_read_b32 v78, v78
	v_add_u32_e32 v82, s6, v121
	ds_read_b32 v82, v82
	v_sub_f32_e32 v76, v76, v86
	v_fma_f32 v178, v76, v95, v86
	s_waitcnt lgkmcnt(1)
	v_add_f32_e32 v78, v45, v78
	v_max_f32_e64 v83, -v78, 0
	v_mul_f32_e64 v78, |v78|, s1
	v_exp_f32_e32 v78, v78
	s_waitcnt lgkmcnt(0)
	v_add_f32_e32 v82, v43, v82
	v_mul_f32_e32 v82, 0xbfb8aa3b, v82
	v_exp_f32_e32 v82, v82
	v_add_f32_e32 v78, 1.0, v78
	v_cmp_gt_f32_e32 vcc, s8, v78
	v_add_f32_e32 v82, 1.0, v82
	s_nop 0
	v_cndmask_b32_e64 v84, 0, 32, vcc
	v_ldexp_f32 v78, v78, v84
	v_log_f32_e32 v78, v78
	v_rcp_f32_e32 v82, v82
	v_mul_f32_e32 v84, 0x3f317217, v78
	v_fma_f32 v84, v78, s9, -v84
	v_fmac_f32_e32 v84, 0x3377d1cf, v78
	v_fmac_f32_e32 v84, 0x3f317217, v78
	v_cmp_lt_f32_e64 s[64:65], |v78|, s10
	s_nop 1
	v_cndmask_b32_e64 v78, v78, v84, s[64:65]
	v_cndmask_b32_e32 v84, 0, v147, vcc
	v_sub_f32_e32 v78, v78, v84
	v_add_f32_e32 v78, v83, v78
	v_sub_f32_e32 v78, -0.5, v78
	v_mul_f32_e32 v78, 0x3fb8aa3b, v78
	v_exp_f32_e32 v78, v78
	v_add_u32_e32 v83, s6, v122
	ds_read_b32 v83, v83
	v_lshlrev_b32_e32 v84, 16, v169
	v_sub_f32_e32 v179, v176, v78
	v_add_u32_e32 v78, s33, v122
	ds_read_b32 v78, v78
	v_pk_mov_b32 v[76:77], v[76:77], v[84:85] op_sel:[1,0]
	s_waitcnt lgkmcnt(0)
; #define LAS __attribute__((address_space(3)))
; __device__ __forceinline__ float sigmoidf_(float x) { return __builtin_amdgcn_rcpf(1.0f + __expf(-x)); }
; __device__ __forceinline__ void rwkv_chunk_group(Frame& F, int bc, unsigned long long& tsub) {
;     ...
;         for (int tt = 0; tt < 8; ++tt) { const int t = tb + tt;
;             const float cr = bf2f(raw[tt + 1][0]), ck = bf2f(raw[tt + 1][1]), cv = bf2f(raw[tt + 1][2]);
;             const float r = cr + (pr - cr) * mur, k = ck + (pk - ck) * muk, v = cv + (pv - cv) * muv; pr = cr; pk = ck; pv = cv;
;             const float wl = *(const LAS float*)(L + L_WL + (t * 65 + ch) * 4), al = *(const LAS float*)(L + L_AL + (t * 65 + ch) * 4), gl = *(const LAS float*)(L + L_GL + (t * 65 + ch) * 4);
;             const float z = -(w0 + wl); const float sp = fmaxf(z, 0.f) + __logf(1.f + __expf(-fabsf(z)));
;             const float lgd = -__expf(-sp - 0.5f);
;             const float ic = sigmoidf_(a0 + al);
;             const float kv = k * k_k; const float kq = k * (1.f + (ic - 1.f) * k_a);
;             kkv[tt] = kv; icv[tt] = ic; sq[tt] = kv * kv; bq[tt] = r * kq * r_k;
;             rr[tt] = r; kp[tt] = kq; vv[tt] = v; run += lgd; ld[tt] = run; ggv[tt] = gl;
;         }
	v_add_f32_e32 v78, v45, v78
	v_max_f32_e64 v87, -v78, 0
	v_mul_f32_e64 v78, |v78|, s1
	v_exp_f32_e32 v78, v78
	v_pk_add_f32 v[76:77], v[76:77], v[84:85] neg_lo:[0,1] neg_hi:[0,1]
	v_add_f32_e32 v78, 1.0, v78
	v_cmp_gt_f32_e32 vcc, s8, v78
	v_pk_fma_f32 v[76:77], v[76:77], v[52:53], v[84:85] op_sel_hi:[1,0,1]
	s_nop 0
	v_cndmask_b32_e64 v88, 0, 32, vcc
	v_ldexp_f32 v78, v78, v88
	v_log_f32_e32 v78, v78
	s_nop 0
	v_mul_f32_e32 v88, 0x3f317217, v78
	v_fma_f32 v88, v78, s9, -v88
	v_fmac_f32_e32 v88, 0x3377d1cf, v78
	v_fmac_f32_e32 v88, 0x3f317217, v78
	v_cmp_lt_f32_e64 s[64:65], |v78|, s10
	s_nop 1
	v_cndmask_b32_e64 v78, v78, v88, s[64:65]
	v_cndmask_b32_e32 v88, 0, v147, vcc
	v_sub_f32_e32 v78, v78, v88
	v_add_f32_e32 v78, v87, v78
	v_sub_f32_e32 v78, -0.5, v78
	v_mul_f32_e32 v78, 0x3fb8aa3b, v78
	v_exp_f32_e32 v87, v78
	v_add_f32_e32 v78, v43, v83
	v_mul_f32_e32 v78, 0xbfb8aa3b, v78
	v_exp_f32_e32 v78, v78
	v_sub_f32_e32 v181, v179, v87
	v_lshlrev_b32_e32 v87, 16, v158
	v_sub_f32_e32 v86, v86, v87
	v_add_f32_e32 v78, 1.0, v78
	v_rcp_f32_e32 v83, v78
	v_pk_mov_b32 v[78:79], v[78:79], v[90:91] op_sel:[1,0]
	v_fma_f32 v180, v86, v95, v87
	v_pk_add_f32 v[78:79], v[78:79], v[90:91] neg_lo:[0,1] neg_hi:[0,1]
	v_add_u32_e32 v86, s33, v123
	v_pk_fma_f32 v[88:89], v[78:79], v[42:43], v[90:91] op_sel_hi:[1,0,1]
	v_pk_add_f32 v[78:79], v[82:83], -1.0 op_sel_hi:[1,0]
	ds_read_b32 v86, v86
	v_pk_fma_f32 v[78:79], v[46:47], v[78:79], 1.0 op_sel_hi:[0,1,0]
	v_pk_mul_f32 v[78:79], v[88:89], v[78:79]
	s_nop 0
	v_mul_f32_e32 v92, v175, v78
	v_mul_f32_e32 v187, v103, v92
	v_mul_f32_e32 v92, v178, v79
	v_mul_f32_e32 v186, v103, v92
	v_add_u32_e32 v92, s6, v123
	ds_read_b32 v92, v92
	s_waitcnt lgkmcnt(1)
	v_add_f32_e32 v86, v45, v86
	v_max_f32_e64 v93, -v86, 0
	v_mul_f32_e64 v86, |v86|, s1
	v_exp_f32_e32 v86, v86
	s_nop 0
	v_add_f32_e32 v86, 1.0, v86
	v_cmp_gt_f32_e32 vcc, s8, v86
	s_nop 1
	v_cndmask_b32_e64 v94, 0, 32, vcc
	v_ldexp_f32 v86, v86, v94
	v_log_f32_e32 v86, v86
	s_nop 0
	v_mul_f32_e32 v94, 0x3f317217, v86
	v_fma_f32 v94, v86, s9, -v94
	v_fmac_f32_e32 v94, 0x3377d1cf, v86
	v_fmac_f32_e32 v94, 0x3f317217, v86
	v_cmp_lt_f32_e64 s[64:65], |v86|, s10
	s_nop 1
	v_cndmask_b32_e64 v86, v86, v94, s[64:65]
	v_cndmask_b32_e32 v94, 0, v147, vcc
	v_sub_f32_e32 v86, v86, v94
	v_lshlrev_b32_e32 v94, 16, v159
	v_sub_f32_e32 v87, v87, v94
	v_fma_f32 v183, v87, v95, v94
	v_add_u32_e32 v87, s33, v124
	ds_read_b32 v87, v87
	v_add_f32_e32 v86, v93, v86
	v_sub_f32_e32 v86, -0.5, v86
	v_mul_f32_e32 v86, 0x3fb8aa3b, v86
	v_exp_f32_e32 v93, v86
	s_waitcnt lgkmcnt(0)
	v_add_f32_e32 v87, v45, v87
	v_max_f32_e64 v97, -v87, 0
	v_mul_f32_e64 v87, |v87|, s1
	v_exp_f32_e32 v87, v87
	v_add_f32_e32 v86, v43, v92
	v_mul_f32_e32 v86, 0xbfb8aa3b, v86
	v_exp_f32_e32 v86, v86
	v_add_f32_e32 v87, 1.0, v87
	v_cmp_gt_f32_e32 vcc, s8, v87
	v_sub_f32_e32 v184, v181, v93
	v_add_f32_e32 v86, 1.0, v86
	v_cndmask_b32_e64 v98, 0, 32, vcc
	v_ldexp_f32 v87, v87, v98
	v_log_f32_e32 v87, v87
	v_rcp_f32_e32 v86, v86
	v_sub_f32_e32 v94, v94, v197
	v_and_b32_e32 v93, 0xffff0000, v171
	v_mul_f32_e32 v98, 0x3f317217, v87
	v_fma_f32 v98, v87, s9, -v98
	v_fmac_f32_e32 v98, 0x3377d1cf, v87
	v_fmac_f32_e32 v98, 0x3f317217, v87
	v_cmp_lt_f32_e64 s[64:65], |v87|, s10
	v_lshlrev_b32_e32 v92, 16, v171
	v_pk_mov_b32 v[84:85], v[84:85], v[92:93] op_sel:[1,0]
	v_cndmask_b32_e64 v87, v87, v98, s[64:65]
	v_cndmask_b32_e32 v98, 0, v147, vcc
	v_sub_f32_e32 v87, v87, v98
	v_add_f32_e32 v87, v97, v87
	v_sub_f32_e32 v87, -0.5, v87
	v_mul_f32_e32 v87, 0x3fb8aa3b, v87
	v_exp_f32_e32 v188, v87
	v_add_f32_e32 v87, v43, v96
	v_mul_f32_e32 v87, 0xbfb8aa3b, v87
	v_exp_f32_e32 v87, v87
	v_and_b32_e32 v97, 0xffff0000, v170
	v_lshlrev_b32_e32 v96, 16, v170
	v_pk_mov_b32 v[90:91], v[90:91], v[96:97] op_sel:[1,0]
	v_add_f32_e32 v87, 1.0, v87
	v_rcp_f32_e32 v87, v87
	v_pk_add_f32 v[90:91], v[90:91], v[96:97] neg_lo:[0,1] neg_hi:[0,1]
	v_pk_add_f32 v[84:85], v[84:85], v[92:93] neg_lo:[0,1] neg_hi:[0,1]
	v_pk_fma_f32 v[98:99], v[90:91], v[42:43], v[96:97] op_sel_hi:[1,0,1]
	v_pk_add_f32 v[90:91], v[86:87], -1.0 op_sel_hi:[1,0]
	v_pk_fma_f32 v[84:85], v[84:85], v[52:53], v[92:93] op_sel_hi:[1,0,1]
	v_pk_fma_f32 v[90:91], v[46:47], v[90:91], 1.0 op_sel_hi:[0,1,0]
	v_pk_mul_f32 v[90:91], v[98:99], v[90:91]
	s_nop 0
	v_mul_f32_e32 v190, v180, v90
	v_mul_f32_e32 v196, v103, v190
	v_mul_f32_e32 v190, v183, v91
	v_mul_f32_e32 v195, v103, v190
	v_sub_f32_e32 v190, v184, v188
	v_fma_f32 v188, v94, v95, v197
	v_add_u32_e32 v94, s33, v125
	ds_read_b32 v94, v94
	v_permlane32_swap_b32_e32 v101, v196
	v_permlane32_swap_b32_e32 v100, v195
	s_waitcnt lgkmcnt(0)
	v_add_f32_e32 v94, v45, v94
	v_max_f32_e64 v192, -v94, 0
	v_mul_f32_e64 v94, |v94|, s1
	v_exp_f32_e32 v94, v94
	v_add_f32_e32 v201, v101, v196
	v_add_f32_e32 v195, v100, v195
	v_add_f32_e32 v94, 1.0, v94
	v_cmp_gt_f32_e32 vcc, s8, v94
	s_nop 1
	v_cndmask_b32_e64 v198, 0, 32, vcc
	v_ldexp_f32 v94, v94, v198
	v_log_f32_e32 v94, v94
	s_nop 0
	v_mul_f32_e32 v198, 0x3f317217, v94
	v_fma_f32 v198, v94, s9, -v198
	v_fmac_f32_e32 v198, 0x3377d1cf, v94
	v_fmac_f32_e32 v198, 0x3f317217, v94
	v_cmp_lt_f32_e64 s[64:65], |v94|, s10
	s_nop 1
	v_cndmask_b32_e64 v94, v94, v198, s[64:65]
	v_cndmask_b32_e32 v198, 0, v147, vcc
	v_sub_f32_e32 v94, v94, v198
	v_lshlrev_b32_e32 v198, 16, v172
	v_pk_mov_b32 v[92:93], v[92:93], v[198:199] op_sel:[1,0]
	v_add_f32_e32 v94, v192, v94
	v_pk_add_f32 v[92:93], v[92:93], v[198:199] neg_lo:[0,1] neg_hi:[0,1]
	v_sub_f32_e32 v94, -0.5, v94
	v_pk_fma_f32 v[92:93], v[92:93], v[52:53], v[198:199] op_sel_hi:[1,0,1]
	v_add_u32_e32 v52, s33, v126
	ds_read_b32 v52, v52
	v_mul_f32_e32 v94, 0x3fb8aa3b, v94
	v_exp_f32_e32 v192, v94
	v_add_f32_e32 v94, v43, v191
	v_lshlrev_b32_e32 v191, 16, v163
	v_sub_f32_e32 v197, v197, v191
	v_fmac_f32_e32 v191, v197, v95
	v_add_u32_e32 v95, s6, v126
	v_add_u32_e32 v197, s7, v126
	ds_read_b32 v95, v95
	ds_read_b32 v200, v197
	s_waitcnt lgkmcnt(2)
; #define GAS __attribute__((address_space(1)))
; #define LAS __attribute__((address_space(3)))
; __device__ __forceinline__ unsigned pk2(float lo, float hi) { f32x2_k v = {lo, hi}; bf16x2_k b = __builtin_convertvector(v, bf16x2_k); return __builtin_bit_cast(unsigned, b); }
; __device__ __forceinline__ void rwkv_chunk_group(Frame& F, int bc, unsigned long long& tsub) {
;     ...
;         wave_sum8(sq); wave_sum8(bq);
; #pragma unroll
;         for (int tt = 0; tt < 8; ++tt) { const float kn = kkv[tt] * __builtin_amdgcn_rsqf(fmaxf(sq[tt], 1e-24f));
;             aa[tt] = -kn; bb[tt] = kn * icv[tt]; vbv[tt] = bq[tt] * vv[tt]; }
;         *(LAS float*)(L + L_GT + (w * 64 + ch) * 4) = run;
;         *(GAS v4u*)(VBp + ch * 64 + tb) = (v4u){pk2(vbv[0], vbv[1]), pk2(vbv[2], vbv[3]), pk2(vbv[4], vbv[5]), pk2(vbv[6], vbv[7])};
;         *(GAS v4u*)(Gp + ch * 64 + tb) = (v4u){pk2(ggv[0], ggv[1]), pk2(ggv[2], ggv[3]), pk2(ggv[4], ggv[5]), pk2(ggv[6], ggv[7])};
;         if (hh + 1 < RW_H) {
;             const bool has = (c * CH + tb > 0);
; #pragma unroll
;             for (int tt = 0; tt < 9; ++tt) { const size_t off = (size_t)(row0 + tb + tt - 1) * PRW + hnext * 64 + ch;
;                 if (tt > 0 || has) { raw[tt][0] = P[off]; raw[tt][1] = P[off + 512]; raw[tt][2] = P[off + 1024]; } }
	v_add_f32_e32 v45, v45, v52
	v_max_f32_e64 v52, -v45, 0
	v_mul_f32_e64 v45, |v45|, s1
	v_exp_f32_e32 v45, v45
	s_waitcnt lgkmcnt(1)
	v_add_f32_e32 v43, v43, v95
	v_mul_f32_e32 v94, 0xbfb8aa3b, v94
	v_mul_f32_e32 v43, 0xbfb8aa3b, v43
	v_add_f32_e32 v45, 1.0, v45
	v_cmp_gt_f32_e32 vcc, s8, v45
	v_exp_f32_e32 v94, v94
	v_exp_f32_e32 v43, v43
	v_cndmask_b32_e64 v197, 0, 32, vcc
	v_ldexp_f32 v45, v45, v197
	v_log_f32_e32 v45, v45
	v_add_f32_e32 v94, 1.0, v94
	v_add_f32_e32 v43, 1.0, v43
	v_rcp_f32_e32 v94, v94
	v_mul_f32_e32 v197, 0x3f317217, v45
	v_fma_f32 v197, v45, s9, -v197
	v_fmac_f32_e32 v197, 0x3377d1cf, v45
	v_fmac_f32_e32 v197, 0x3f317217, v45
	v_cmp_lt_f32_e64 s[64:65], |v45|, s10
	v_rcp_f32_e32 v95, v43
	v_sub_f32_e32 v192, v190, v192
	v_cndmask_b32_e64 v45, v45, v197, s[64:65]
	v_cndmask_b32_e32 v197, 0, v147, vcc
	v_sub_f32_e32 v45, v45, v197
	v_add_f32_e32 v45, v52, v45
	v_sub_f32_e32 v45, -0.5, v45
	v_mul_f32_e32 v45, 0x3fb8aa3b, v45
	v_exp_f32_e32 v45, v45
	s_nop 0
	v_pk_mul_f32 v[100:101], v[80:81], v[44:45] op_sel_hi:[1,0]
	v_pk_mul_f32 v[80:81], v[98:99], v[44:45] op_sel_hi:[1,0]
	v_pk_mul_f32 v[196:197], v[100:101], v[100:101]
	v_pk_mul_f32 v[98:99], v[80:81], v[80:81]
	v_sub_f32_e32 v52, v192, v45
	s_nop 0
	v_permlane32_swap_b32_e32 v196, v98
	v_permlane32_swap_b32_e32 v197, v99
	v_add_f32_e32 v196, v196, v98
	v_add_f32_e32 v197, v197, v99
	v_lshlrev_b32_e32 v98, 16, v165
	v_and_b32_e32 v99, 0xffff0000, v165
	v_pk_mov_b32 v[96:97], v[96:97], v[98:99] op_sel:[1,0]
	v_pk_mul_f32 v[88:89], v[88:89], v[44:45] op_sel_hi:[1,0]
	v_pk_add_f32 v[96:97], v[96:97], v[98:99] neg_lo:[0,1] neg_hi:[0,1]
	v_pk_mul_f32 v[198:199], v[88:89], v[88:89]
	v_pk_fma_f32 v[42:43], v[96:97], v[42:43], v[98:99] op_sel_hi:[1,0,1]
	v_pk_add_f32 v[98:99], v[94:95], -1.0 op_sel_hi:[1,0]
	v_pk_mul_f32 v[44:45], v[42:43], v[44:45] op_sel_hi:[1,0]
	v_pk_fma_f32 v[98:99], v[46:47], v[98:99], 1.0 op_sel_hi:[0,1,0]
	v_pk_mul_f32 v[42:43], v[42:43], v[98:99]
	v_pk_mul_f32 v[96:97], v[44:45], v[44:45]
	v_mul_f32_e32 v46, v188, v42
	v_mul_f32_e32 v46, v103, v46
	s_nop 1
	v_permlane32_swap_b32_e32 v187, v46
	v_add_f32_e32 v46, v187, v46
	v_mul_f32_e32 v98, v191, v43
	s_nop 0
	v_permlane16_swap_b32_e32 v201, v46
	v_mul_f32_e32 v98, v103, v98
	v_add_f32_e32 v46, v201, v46
	s_nop 0
	v_permlane32_swap_b32_e32 v186, v98
	v_add_f32_dpp v46, v46, v46 quad_perm:[1,0,3,2] row_mask:0xf bank_mask:0xf bound_ctrl:1
	v_add_f32_e32 v98, v186, v98
	s_nop 1
	v_permlane16_swap_b32_e32 v195, v98
	v_add_f32_dpp v46, v46, v46 quad_perm:[2,3,0,1] row_mask:0xf bank_mask:0xf bound_ctrl:1
	v_add_f32_e32 v98, v195, v98
	v_permlane32_swap_b32_e32 v198, v96
	v_add_f32_dpp v46, v46, v46 row_half_mirror row_mask:0xf bank_mask:0xf bound_ctrl:1
	v_permlane32_swap_b32_e32 v199, v97
	s_nop 0
	v_add_f32_dpp v46, v46, v46 row_mirror row_mask:0xf bank_mask:0xf bound_ctrl:1
	v_add_f32_dpp v98, v98, v98 quad_perm:[1,0,3,2] row_mask:0xf bank_mask:0xf bound_ctrl:1
	v_readlane_b32 s14, v46, 0
	v_readlane_b32 s64, v46, 16
	v_readlane_b32 s72, v46, 32
	v_readlane_b32 s96, v46, 48
	v_add_f32_e32 v46, v198, v96
	v_add_f32_e32 v96, v199, v97
	v_add_f32_dpp v98, v98, v98 quad_perm:[2,3,0,1] row_mask:0xf bank_mask:0xf bound_ctrl:1
	v_permlane16_swap_b32_e32 v196, v46
	v_permlane16_swap_b32_e32 v197, v96
	v_add_f32_dpp v98, v98, v98 row_half_mirror row_mask:0xf bank_mask:0xf bound_ctrl:1
	v_add_f32_e32 v46, v196, v46
	v_add_f32_e32 v96, v197, v96
	v_add_f32_dpp v98, v98, v98 row_mirror row_mask:0xf bank_mask:0xf bound_ctrl:1
	v_add_f32_dpp v46, v46, v46 quad_perm:[1,0,3,2] row_mask:0xf bank_mask:0xf bound_ctrl:1
	v_add_f32_dpp v96, v96, v96 quad_perm:[1,0,3,2] row_mask:0xf bank_mask:0xf bound_ctrl:1
	v_readlane_b32 s73, v98, 32
	v_add_f32_dpp v46, v46, v46 quad_perm:[2,3,0,1] row_mask:0xf bank_mask:0xf bound_ctrl:1
	v_add_f32_dpp v96, v96, v96 quad_perm:[2,3,0,1] row_mask:0xf bank_mask:0xf bound_ctrl:1
	v_readlane_b32 s15, v98, 0
	v_readlane_b32 s65, v98, 16
	v_readlane_b32 s97, v98, 48
	v_add_f32_dpp v46, v46, v46 row_half_mirror row_mask:0xf bank_mask:0xf bound_ctrl:1
	v_add_f32_dpp v96, v96, v96 row_half_mirror row_mask:0xf bank_mask:0xf bound_ctrl:1
	v_pk_mul_f32 v[196:197], v[84:85], s[72:73]
	s_lshl_b64 s[72:73], s[66:67], 13
	v_pk_mul_f32 v[98:99], v[36:37], s[14:15]
	v_pk_mul_f32 v[186:187], v[76:77], s[64:65]
	v_add_f32_dpp v46, v46, v46 row_mirror row_mask:0xf bank_mask:0xf bound_ctrl:1
	v_add_f32_dpp v96, v96, v96 row_mirror row_mask:0xf bank_mask:0xf bound_ctrl:1
	v_pk_mul_f32 v[198:199], v[92:93], s[96:97]
	v_readlane_b32 s15, v254, 39
	s_cmp_eq_u32 s68, 7
	v_readlane_b32 s93, v46, 0
	v_readlane_b32 s71, v46, 16
	v_readlane_b32 s69, v46, 32
	v_readlane_b32 s64, v46, 48
	v_readlane_b32 s14, v96, 0
	v_readlane_b32 s77, v96, 16
	v_readlane_b32 s70, v96, 32
	v_readlane_b32 s65, v96, 48
	v_add_u32_e32 v46, s15, v105
	v_cvt_pk_bf16_f32 v96, v98, v99
	v_cvt_pk_bf16_f32 v97, v186, v187
	v_cvt_pk_bf16_f32 v98, v196, v197
	v_cvt_pk_bf16_f32 v99, v198, v199
	v_lshl_add_u64 v[186:187], v[62:63], 0, s[72:73]
	s_cselect_b64 s[96:97], -1, 0
	ds_write_b32 v46, v52
	global_store_dwordx4 v[186:187], v[96:99], off
	s_and_b64 vcc, exec, s[96:97]
	s_nop 0
	v_cvt_pk_bf16_f32 v96, v47, v177
	v_cvt_pk_bf16_f32 v97, v182, v185
	v_cvt_pk_bf16_f32 v98, v189, v193
	s_waitcnt lgkmcnt(1)
	v_cvt_pk_bf16_f32 v99, v194, v200
	v_lshl_add_u64 v[46:47], v[64:65], 0, s[72:73]
	global_store_dwordx4 v[46:47], v[96:99], off
	s_cbranch_vccnz .LBB0_1416
	v_readlane_b32 s72, v254, 60
	s_lshl_b32 s94, s13, 7
	v_readlane_b32 s73, v254, 61
	v_lshl_add_u64 v[46:47], v[56:57], 0, s[94:95]
	s_andn2_b64 vcc, exec, s[72:73]
	s_cbranch_vccnz .LBB0_1415
	v_readlane_b32 s72, v254, 62
	v_readlane_b32 s73, v254, 63
	s_nop 1
	v_lshl_add_u64 v[96:97], v[46:47], 0, s[72:73]
	global_load_ushort v153, v[96:97], off
	global_load_ushort v202, v[96:97], off offset:1024
	global_load_ushort v215, v[96:97], off offset:2048
